# comb3 + SwiGLU epilogue: row rstd precomputed one unit ahead (4 PART loads per wave instead of 16) and exchanged through LDS
# speedup vs baseline: 1.0240x; 1.0147x over previous
; __global__ void __launch_bounds__(NTHR, 2) fwd_megakernel(Args args) {
;     ...
;     const int lo = args.ph_lo, hi = args.ph_hi; const bool coop = args.coop != 0;
;     unsigned char* ws = args.ws;
;     bf16_t* W1IN = (bf16_t*)(ws + WS_W1IN); bf16_t* W1OUT = (bf16_t*)(ws + WS_W1OUT); bf16_t* W2IN = (bf16_t*)(ws + WS_W2IN); bf16_t* W2OUT = (bf16_t*)(ws + WS_W2OUT);
;     bf16_t* WMIXIN = (bf16_t*)(ws + WS_WMIXIN); bf16_t* WMIXOUT = (bf16_t*)(ws + WS_WMIXOUT); bf16_t* WKV = (bf16_t*)(ws + WS_WKV); bf16_t* WO = (bf16_t*)(ws + WS_WO);
;     bf16_t* WSGU = (bf16_t*)(ws + WS_WSGU); bf16_t* MEMN = (bf16_t*)(ws + WS_MEMN); bf16_t* KV = (bf16_t*)(ws + WS_KMAT);     bf16_t* VWOT = (bf16_t*)(ws + WS_XR); bf16_t* QKT = (bf16_t*)(ws + WS_XR + 8 * MiB);     bf16_t* WQN = (bf16_t*)(ws + WS_WQ);
;     float* PART = (float*)(ws + WS_PART); float* VSTAT = (float*)(ws + WS_VSTAT); bf16_t* XB = (bf16_t*)(ws + WS_XB); bf16_t* ACT = (bf16_t*)(ws + WS_ACT);
;     bf16_t* AB = (bf16_t*)(ws + WS_AB); bf16_t* UB = (bf16_t*)(ws + WS_UB); bf16_t* VB = (bf16_t*)(ws + WS_VB); bf16_t* Y = (bf16_t*)(ws + WS_Y);
;     bf16_t* P = (bf16_t*)(ws + WS_P);
;     ...
;     volatile LAS unsigned* bst = (volatile LAS unsigned*)(lds + LDS_BYTES - 64);
;     if (tid < 16) bst[tid] = 0u;
;     __syncthreads();
;     XcdBarrier xbar; xbar.bar = (unsigned*)(ws + WS_CTL); xbar.x = 0; xbar.st = bst;
;     if (coop) xbar = xcd_barrier_post((unsigned*)(ws + WS_CTL), bst);
;     if (args.coop == 2) grid.sync();
;     ...
;     if (IN(0)) { const int kz = opaque0();
;         LAS float* scr = (LAS float*)(lds + wave * 16640);
;         const int gw = bid * NWAVES + wave, NGW = G * NWAVES;
;         constexpr int I_FIN = (D / 64) * (2 * FF / 64), I_FOUT = (FF / 64) * (D / 64), I_MIN = (D / 64) * (4096 / 64), I_SQ = (D / 64) * (D / 64), I_KV = (D / 64) * (4096 / 64);
;         constexpr int NITEMS = 2 * I_FIN + 2 * I_FOUT + I_MIN + 2 * I_SQ + I_KV;
;         const float *w_f1i = KIN(I_FFN1_WIN), *w_f2i = KIN(I_FFN2_WIN), *w_f1o = KIN(I_FFN1_WOUT), *w_f2o = KIN(I_FFN2_WOUT), *w_mi = KIN(I_WMIXIN), *w_mo = KIN(I_WMIXOUT), *w_q = KIN(I_WQ), *w_o = KIN(I_WO), *w_kv = KIN(I_WKV);
;         const float *g_f1 = KIN(I_FFN1_NORM), *g_f2 = KIN(I_FFN2_NORM), *g_mi = KIN(I_MIX_NORM), *g_xa = KIN(I_XATTN_NORM);
;     ...
;         {
;             const int nit0 = (G == 256) ? NITEMS - I_FIN - 2 * I_FOUT : NITEMS;
.LBB0_19:
	s_mov_b32 s99, 0
	s_lshr_b32 s95, s11, 6
	s_add_u32 s58, s14, 0x2c00000
	s_addc_u32 s59, s15, 0
	s_add_u32 s8, s14, 0x4200000
	s_addc_u32 s9, s15, 0
	s_add_u32 s2, s14, 0x6e00000
	s_addc_u32 s3, s15, 0
	s_add_u32 s56, s14, 0x8400000
	s_addc_u32 s57, s15, 0
	s_add_u32 s54, s14, 0x9400000
	s_addc_u32 s55, s15, 0
	s_add_u32 s62, s14, 0xa400000
	s_addc_u32 s63, s15, 0
	s_add_u32 s52, s14, 0xb400000
	s_addc_u32 s53, s15, 0
	s_add_u32 s60, s14, 0x9c00000
	s_addc_u32 s61, s15, 0
	s_add_u32 s48, s14, 0xc300000
	s_addc_u32 s49, s15, 0
	s_add_u32 s50, s14, 0xc500000
	s_addc_u32 s51, s15, 0
	v_writelane_b32 v254, s11, 3
	s_cmp_lt_i32 s16, 1
	v_writelane_b32 v254, s2, 4
	s_cselect_b64 s[64:65], -1, 0
	s_cmp_gt_i32 s17, 0
	v_writelane_b32 v254, s3, 5
	s_cselect_b64 s[2:3], -1, 0
	s_and_b64 s[2:3], s[64:65], s[2:3]
	v_and_b32_e32 v220, 63, v221
	s_andn2_b64 vcc, exec, s[2:3]
	s_mov_b32 s86, 0
	v_writelane_b32 v254, s92, 6
	s_nop 1
	v_writelane_b32 v254, s93, 7
	s_cbranch_vccnz .LBB0_173
	s_lshl_b32 s2, s10, 3
	s_mov_b32 s84, 0
	s_add_i32 s66, s95, s2
	s_ashr_i32 s85, s84, 31
	s_add_u32 s2, s0, s84
	s_addc_u32 s3, s1, s85
	s_load_dwordx8 s[36:43], s[2:3], 0x10
	s_load_dwordx4 s[28:31], s[2:3], 0xc0
	s_load_dwordx8 s[20:27], s[2:3], 0xa0
	s_load_dwordx2 s[70:71], s[2:3], 0x30
	s_load_dwordx4 s[4:7], s[2:3], 0x88
	s_cmpk_eq_i32 s34, 0x100
	s_movk_i32 s2, 0x2e00
	s_cselect_b32 s67, s2, 0x5a00
	s_cmp_lt_i32 s66, s67
	s_cselect_b64 s[68:69], -1, 0
	s_cmp_ge_i32 s66, s67
	s_cbranch_scc1 .LBB0_29
	s_cmpk_lt_i32 s66, 0x1600
	s_mov_b32 s89, 1
	s_cbranch_scc1 .LBB0_30
	s_cmpk_gt_u32 s66, 0x1dff
	s_cbranch_scc0 .LBB0_31
	s_cmpk_gt_u32 s66, 0x25ff
	s_cbranch_scc0 .LBB0_32
	s_cmpk_gt_u32 s66, 0x29ff
	s_cbranch_scc0 .LBB0_33
	s_cmpk_gt_u32 s66, 0x2dff
	s_cbranch_scc0 .LBB0_34
	s_cmpk_gt_u32 s66, 0x38ff
	s_cbranch_scc0 .LBB0_35
	s_cmpk_gt_u32 s66, 0x4eff
	s_cbranch_scc0 .LBB0_36
	s_add_i32 s88, s66, 0xffffb100
	s_mov_b64 s[72:73], 0
	s_mov_b64 s[74:75], 0
	s_waitcnt lgkmcnt(0)
	s_mov_b64 s[2:3], s[30:31]
	s_branch .LBB0_37

; __device__ __forceinline__ void load_rstd(const float* part, int row0, int fq, float (&rs)[2][4]) {
; #pragma unroll
;     for (int ai = 0; ai < 2; ++ai)
; #pragma unroll
;         for (int m = 0; m < 4; ++m) { const float* p = part + (size_t)(row0 + ai * HALF + m * 16) * NPART + fq * 8;
;             const f32x4 a = *(const f32x4*)p, b = *(const f32x4*)(p + 4); float s = ((a[0] + a[1]) + (a[2] + a[3])) + ((b[0] + b[1]) + (b[2] + b[3]));
;             s += __shfl_xor(s, 16); s += __shfl_xor(s, 32); rs[ai][m] = rsqrtf(s * (1.0f / D) + RMS_EPS); }
.LBB0_264:
	s_bitcmp1_b32 s99, 1
	s_cbranch_scc1 .Lswg_rs_SWG_LBB0_264
	v_lshl_add_u32 v249, s11, 8, v192
	s_mov_b64 vcc, 0x1000
	s_mov_b64 s[100:101], 0x4000
	v_ashrrev_i32_e32 v179, 31, v249
	v_mov_b32_e32 v178, v249
	v_lshlrev_b64 v[178:179], 7, v[178:179]
	v_lshl_add_u64 v[178:179], v[152:153], 0, v[178:179]
	v_lshl_add_u64 v[234:235], v[178:179], 0, vcc
	v_lshl_add_u64 v[236:237], v[178:179], 0, s[100:101]
	v_lshl_add_u64 v[238:239], v[236:237], 0, vcc
	global_load_dwordx4 v[128:131], v[178:179], off
	global_load_dwordx4 v[132:135], v[178:179], off offset:16
	global_load_dwordx4 v[136:139], v[178:179], off offset:2048
	global_load_dwordx4 v[140:143], v[178:179], off offset:2064
	global_load_dwordx4 v[162:165], v[234:235], off
	global_load_dwordx4 v[166:169], v[234:235], off offset:16
	global_load_dwordx4 v[170:173], v[234:235], off offset:2048
	global_load_dwordx4 v[174:177], v[234:235], off offset:2064
	global_load_dwordx4 v[200:203], v[236:237], off
	global_load_dwordx4 v[204:207], v[236:237], off offset:16
	global_load_dwordx4 v[208:211], v[236:237], off offset:2048
	global_load_dwordx4 v[212:215], v[236:237], off offset:2064
	global_load_dwordx4 v[216:219], v[238:239], off
	global_load_dwordx4 v[222:225], v[238:239], off offset:16
	global_load_dwordx4 v[226:229], v[238:239], off offset:2048
	global_load_dwordx4 v[230:233], v[238:239], off offset:2064
	v_mov_b32_e32 v248, 0xbfb8aa3b
	v_mov_b32_e32 v250, 0x358637bd
	v_lshl_or_b32 v251, s92, 7, v194
	v_lshlrev_b32_e32 v251, 1, v251
	v_mul_u32_u24_e32 v249, 0x2c00, v249
	v_add_u32_e32 v251, v251, v249
	s_waitcnt vmcnt(0)
	v_add_f32_e32 v128, v128, v129
	v_add_f32_e32 v130, v130, v131
	v_add_f32_e32 v132, v132, v133
	v_add_f32_e32 v134, v134, v135
	v_add_f32_e32 v136, v136, v137
	v_add_f32_e32 v138, v138, v139
	v_add_f32_e32 v140, v140, v141
	v_add_f32_e32 v142, v142, v143
	v_add_f32_e32 v162, v162, v163
	v_add_f32_e32 v164, v164, v165
	v_add_f32_e32 v166, v166, v167
	v_add_f32_e32 v168, v168, v169
	v_add_f32_e32 v170, v170, v171
	v_add_f32_e32 v172, v172, v173
	v_add_f32_e32 v174, v174, v175
	v_add_f32_e32 v176, v176, v177
	v_add_f32_e32 v200, v200, v201
	v_add_f32_e32 v202, v202, v203
	v_add_f32_e32 v204, v204, v205
	v_add_f32_e32 v206, v206, v207
	v_add_f32_e32 v208, v208, v209
	v_add_f32_e32 v210, v210, v211
	v_add_f32_e32 v212, v212, v213
	v_add_f32_e32 v214, v214, v215
	v_add_f32_e32 v216, v216, v217
	v_add_f32_e32 v218, v218, v219
	v_add_f32_e32 v222, v222, v223
	v_add_f32_e32 v224, v224, v225
	v_add_f32_e32 v226, v226, v227
	v_add_f32_e32 v228, v228, v229
	v_add_f32_e32 v230, v230, v231
	v_add_f32_e32 v232, v232, v233
	v_add_f32_e32 v128, v128, v130
	v_add_f32_e32 v132, v132, v134
	v_add_f32_e32 v136, v136, v138
	v_add_f32_e32 v140, v140, v142
	v_add_f32_e32 v162, v162, v164
	v_add_f32_e32 v166, v166, v168
	v_add_f32_e32 v170, v170, v172
	v_add_f32_e32 v174, v174, v176
	v_add_f32_e32 v200, v200, v202
	v_add_f32_e32 v204, v204, v206
	v_add_f32_e32 v208, v208, v210
	v_add_f32_e32 v212, v212, v214
	v_add_f32_e32 v216, v216, v218
	v_add_f32_e32 v222, v222, v224
	v_add_f32_e32 v226, v226, v228
	v_add_f32_e32 v230, v230, v232
	v_add_f32_e32 v128, v128, v132
	v_add_f32_e32 v136, v136, v140
	v_add_f32_e32 v162, v162, v166
	v_add_f32_e32 v170, v170, v174
	v_add_f32_e32 v200, v200, v204
	v_add_f32_e32 v208, v208, v212
	v_add_f32_e32 v216, v216, v222
	v_add_f32_e32 v226, v226, v230
	v_mov_b32_e32 v179, v128
	v_mov_b32_e32 v235, v136
	v_mov_b32_e32 v237, v162
	v_mov_b32_e32 v239, v170
	v_mov_b32_e32 v241, v200
	v_mov_b32_e32 v243, v208
	v_mov_b32_e32 v245, v216
	v_mov_b32_e32 v247, v226
	s_nop 1
	v_permlane16_swap_b32_e32 v128, v179
	v_permlane16_swap_b32_e32 v136, v235
	v_permlane16_swap_b32_e32 v162, v237
	v_permlane16_swap_b32_e32 v170, v239
	v_permlane16_swap_b32_e32 v200, v241
	v_permlane16_swap_b32_e32 v208, v243
	v_permlane16_swap_b32_e32 v216, v245
	v_permlane16_swap_b32_e32 v226, v247
	v_add_f32_e32 v128, v128, v179
	v_add_f32_e32 v136, v136, v235
	v_add_f32_e32 v162, v162, v237
	v_add_f32_e32 v170, v170, v239
	v_add_f32_e32 v200, v200, v241
	v_add_f32_e32 v208, v208, v243
	v_add_f32_e32 v216, v216, v245
	v_add_f32_e32 v226, v226, v247
	v_mov_b32_e32 v179, v128
	v_mov_b32_e32 v235, v136
	v_mov_b32_e32 v237, v162
	v_mov_b32_e32 v239, v170
	v_mov_b32_e32 v241, v200
	v_mov_b32_e32 v243, v208
	v_mov_b32_e32 v245, v216
	v_mov_b32_e32 v247, v226
	s_nop 1
	v_permlane32_swap_b32_e32 v128, v179
	v_permlane32_swap_b32_e32 v136, v235
	v_permlane32_swap_b32_e32 v162, v237
	v_permlane32_swap_b32_e32 v170, v239
	v_permlane32_swap_b32_e32 v200, v241
	v_permlane32_swap_b32_e32 v208, v243
	v_permlane32_swap_b32_e32 v216, v245
	v_permlane32_swap_b32_e32 v226, v247
	v_add_f32_e32 v128, v128, v179
	v_add_f32_e32 v136, v136, v235
	v_add_f32_e32 v162, v162, v237
	v_add_f32_e32 v170, v170, v239
	v_add_f32_e32 v200, v200, v241
	v_add_f32_e32 v208, v208, v243
	v_add_f32_e32 v216, v216, v245
	v_add_f32_e32 v226, v226, v247
	v_fmamk_f32 v178, v128, 0x3a000000, v250
	v_fmamk_f32 v234, v136, 0x3a000000, v250
	v_fmamk_f32 v236, v162, 0x3a000000, v250
	v_fmamk_f32 v238, v170, 0x3a000000, v250
	v_fmamk_f32 v240, v200, 0x3a000000, v250
	v_fmamk_f32 v242, v208, 0x3a000000, v250
	v_fmamk_f32 v244, v216, 0x3a000000, v250
	v_fmamk_f32 v246, v226, 0x3a000000, v250
	v_rsq_f32_e32 v178, v178
	v_rsq_f32_e32 v234, v234
	v_rsq_f32_e32 v236, v236
	v_rsq_f32_e32 v238, v238
	v_rsq_f32_e32 v240, v240
	v_rsq_f32_e32 v242, v242
	v_rsq_f32_e32 v244, v244
	v_rsq_f32_e32 v246, v246
	s_branch .Lswg_go_SWG_LBB0_264
; __device__ __forceinline__ unsigned cvt_pk_bf16(float lo, float hi) { unsigned r; asm volatile("v_cvt_pk_bf16_f32 %0, %1, %2" : "=v"(r) : "v"(lo), "v"(hi)); return r; }
; __device__ __forceinline__ float sigmoidf_(float x) { return fast_rcp(1.0f + fast_exp2(-1.4426950408889634f * x)); }
; __device__ __forceinline__ void load_rstd(const float* part, int row0, int fq, float (&rs)[2][4]) {
; #pragma unroll
;     for (int ai = 0; ai < 2; ++ai)
; #pragma unroll
;         for (int m = 0; m < 4; ++m) { const float* p = part + (size_t)(row0 + ai * HALF + m * 16) * NPART + fq * 8;
;             const f32x4 a = *(const f32x4*)p, b = *(const f32x4*)(p + 4); float s = ((a[0] + a[1]) + (a[2] + a[3])) + ((b[0] + b[1]) + (b[2] + b[3]));
;             s += __shfl_xor(s, 16); s += __shfl_xor(s, 32); rs[ai][m] = rsqrtf(s * (1.0f / D) + RMS_EPS); }
;     __device__ __forceinline__ void operator()(const f32x4 (&acc)[2][2][4][2], const Unit& u, int wr, int wc, int fr, int fq) const {
;     ...
;             for (int m = 0; m < 4; ++m) { const float sc = rs[ai][m]; f32x4 o[2];
; #pragma unroll
;                 for (int n = 0; n < 2; ++n) { const f32x4 g = acc[ai][0][m][n] * sc, up = acc[ai][1][m][n] * sc;
; #pragma unroll
;                     for (int e = 0; e < 4; ++e) o[n][e] = g[e] * sigmoidf_(g[e]) * up[e]; }
;                 u32x4 w; w.x = cvt_pk_bf16(o[0][0], o[0][1]); w.y = cvt_pk_bf16(o[0][2], o[0][3]); w.z = cvt_pk_bf16(o[1][0], o[1][1]); w.w = cvt_pk_bf16(o[1][2], o[1][3]);
;                 *(u32x4*)(O + (size_t)(row0 + ai * HALF + m * 16) * FF + col0) = w; }
.Lswg_rs_SWG_LBB0_264:
	v_lshl_add_u32 v249, s11, 8, v192
	v_mov_b32_e32 v248, 0xbfb8aa3b
	v_mov_b32_e32 v250, 0x358637bd
	v_lshl_or_b32 v251, s92, 7, v194
	v_lshlrev_b32_e32 v251, 1, v251
	v_mul_u32_u24_e32 v249, 0x2c00, v249
	v_add_u32_e32 v251, v251, v249
	s_and_b32 s96, s99, 1
	s_lshl_b32 s96, s96, 10
	s_add_i32 s96, s96, 0x21000
	v_lshl_add_u32 v230, v192, 2, s96
	ds_read_b32 v178, v230
	ds_read_b32 v234, v230 offset:64
	ds_read_b32 v236, v230 offset:128
	ds_read_b32 v238, v230 offset:192
	ds_read_b32 v240, v230 offset:512
	ds_read_b32 v242, v230 offset:576
	ds_read_b32 v244, v230 offset:640
	ds_read_b32 v246, v230 offset:704
	s_waitcnt lgkmcnt(0)
.Lswg_go_SWG_LBB0_264:
	s_cmp_lg_u64 s[2:3], 0
	s_cbranch_scc0 .Lswg_np_SWG_LBB0_264
	v_lshrrev_b32_e32 v216, 1, v220
	s_lshl_b32 s96, s91, 8
	s_lshl_b32 s97, s95, 5
	s_add_i32 s96, s96, s97
	v_add_u32_e32 v216, s96, v216
	v_and_b32_e32 v217, 1, v220
	v_lshlrev_b32_e32 v217, 6, v217
	v_lshl_add_u32 v216, v216, 7, v217
	s_add_u32 s96, s14, 0xc300000
	s_addc_u32 s97, s15, 0
	global_load_dwordx4 v[200:203], v216, s[96:97]
	global_load_dwordx4 v[204:207], v216, s[96:97] offset:16
	global_load_dwordx4 v[208:211], v216, s[96:97] offset:32
	global_load_dwordx4 v[212:215], v216, s[96:97] offset:48
.Lswg_np_SWG_LBB0_264:
	v_pk_mul_f32 v[124:125], v[124:125], v[178:179] op_sel_hi:[1,0]
	v_pk_mul_f32 v[126:127], v[126:127], v[178:179] op_sel_hi:[1,0]
	v_pk_mul_f32 v[116:117], v[116:117], v[178:179] op_sel_hi:[1,0]
	v_pk_mul_f32 v[118:119], v[118:119], v[178:179] op_sel_hi:[1,0]
	v_pk_mul_f32 v[108:109], v[108:109], v[234:235] op_sel_hi:[1,0]
	v_pk_mul_f32 v[110:111], v[110:111], v[234:235] op_sel_hi:[1,0]
	v_pk_mul_f32 v[100:101], v[100:101], v[234:235] op_sel_hi:[1,0]
	v_pk_mul_f32 v[102:103], v[102:103], v[234:235] op_sel_hi:[1,0]
	v_pk_mul_f32 v[128:129], v[124:125], v[248:249] op_sel_hi:[1,0]
	v_pk_mul_f32 v[130:131], v[126:127], v[248:249] op_sel_hi:[1,0]
	v_pk_mul_f32 v[132:133], v[116:117], v[248:249] op_sel_hi:[1,0]
	v_pk_mul_f32 v[134:135], v[118:119], v[248:249] op_sel_hi:[1,0]
	v_pk_mul_f32 v[162:163], v[108:109], v[248:249] op_sel_hi:[1,0]
	v_pk_mul_f32 v[164:165], v[110:111], v[248:249] op_sel_hi:[1,0]
	v_pk_mul_f32 v[166:167], v[100:101], v[248:249] op_sel_hi:[1,0]
	v_pk_mul_f32 v[168:169], v[102:103], v[248:249] op_sel_hi:[1,0]
	v_exp_f32_e32 v128, v128
	v_exp_f32_e32 v129, v129
	v_exp_f32_e32 v130, v130
	v_exp_f32_e32 v131, v131
	v_exp_f32_e32 v132, v132
	v_exp_f32_e32 v133, v133
	v_exp_f32_e32 v134, v134
	v_exp_f32_e32 v135, v135
	v_exp_f32_e32 v162, v162
	v_exp_f32_e32 v163, v163
	v_exp_f32_e32 v164, v164
	v_exp_f32_e32 v165, v165
	v_exp_f32_e32 v166, v166
	v_exp_f32_e32 v167, v167
	v_exp_f32_e32 v168, v168
	v_exp_f32_e32 v169, v169
	v_pk_mul_f32 v[120:121], v[120:121], v[178:179] op_sel_hi:[1,0]
	v_pk_mul_f32 v[122:123], v[122:123], v[178:179] op_sel_hi:[1,0]
	v_pk_mul_f32 v[112:113], v[112:113], v[178:179] op_sel_hi:[1,0]
	v_pk_mul_f32 v[114:115], v[114:115], v[178:179] op_sel_hi:[1,0]
	v_pk_mul_f32 v[104:105], v[104:105], v[234:235] op_sel_hi:[1,0]
	v_pk_mul_f32 v[106:107], v[106:107], v[234:235] op_sel_hi:[1,0]
	v_pk_mul_f32 v[96:97], v[96:97], v[234:235] op_sel_hi:[1,0]
	v_pk_mul_f32 v[98:99], v[98:99], v[234:235] op_sel_hi:[1,0]
	v_pk_add_f32 v[128:129], v[128:129], 1.0 op_sel_hi:[1,0]
	v_pk_add_f32 v[130:131], v[130:131], 1.0 op_sel_hi:[1,0]
	v_pk_add_f32 v[132:133], v[132:133], 1.0 op_sel_hi:[1,0]
	v_pk_add_f32 v[134:135], v[134:135], 1.0 op_sel_hi:[1,0]
	v_pk_add_f32 v[162:163], v[162:163], 1.0 op_sel_hi:[1,0]
	v_pk_add_f32 v[164:165], v[164:165], 1.0 op_sel_hi:[1,0]
	v_pk_add_f32 v[166:167], v[166:167], 1.0 op_sel_hi:[1,0]
	v_pk_add_f32 v[168:169], v[168:169], 1.0 op_sel_hi:[1,0]
	v_rcp_f32_e32 v128, v128
	v_rcp_f32_e32 v129, v129
	v_rcp_f32_e32 v130, v130
	v_rcp_f32_e32 v131, v131
	v_rcp_f32_e32 v132, v132
	v_rcp_f32_e32 v133, v133
	v_rcp_f32_e32 v134, v134
	v_rcp_f32_e32 v135, v135
	v_rcp_f32_e32 v162, v162
	v_rcp_f32_e32 v163, v163
	v_rcp_f32_e32 v164, v164
	v_rcp_f32_e32 v165, v165
	v_rcp_f32_e32 v166, v166
	v_rcp_f32_e32 v167, v167
	v_rcp_f32_e32 v168, v168
	v_rcp_f32_e32 v169, v169
	v_mov_b32_e32 v140, v251
	v_add_u32_e32 v174, 0x2c000, v251
	v_pk_mul_f32 v[124:125], v[124:125], v[128:129]
	v_pk_mul_f32 v[126:127], v[126:127], v[130:131]
	v_pk_mul_f32 v[116:117], v[116:117], v[132:133]
	v_pk_mul_f32 v[118:119], v[118:119], v[134:135]
	v_pk_mul_f32 v[108:109], v[108:109], v[162:163]
	v_pk_mul_f32 v[110:111], v[110:111], v[164:165]
	v_pk_mul_f32 v[100:101], v[100:101], v[166:167]
	v_pk_mul_f32 v[102:103], v[102:103], v[168:169]
	v_pk_mul_f32 v[124:125], v[124:125], v[120:121]
	v_pk_mul_f32 v[126:127], v[126:127], v[122:123]
	v_pk_mul_f32 v[116:117], v[116:117], v[112:113]
	v_pk_mul_f32 v[118:119], v[118:119], v[114:115]
	v_pk_mul_f32 v[108:109], v[108:109], v[104:105]
	v_pk_mul_f32 v[110:111], v[110:111], v[106:107]
	v_pk_mul_f32 v[100:101], v[100:101], v[96:97]
	v_pk_mul_f32 v[102:103], v[102:103], v[98:99]
	v_cvt_pk_bf16_f32 v136, v124, v125
	v_cvt_pk_bf16_f32 v137, v126, v127
	v_cvt_pk_bf16_f32 v138, v116, v117
	v_cvt_pk_bf16_f32 v139, v118, v119
	v_cvt_pk_bf16_f32 v170, v108, v109
	v_cvt_pk_bf16_f32 v171, v110, v111
	v_cvt_pk_bf16_f32 v172, v100, v101
	v_cvt_pk_bf16_f32 v173, v102, v103
	global_store_dwordx4 v140, v[136:139], s[28:29]
	global_store_dwordx4 v174, v[170:173], s[28:29]
	s_nop 1
	v_pk_mul_f32 v[92:93], v[92:93], v[236:237] op_sel_hi:[1,0]
	v_pk_mul_f32 v[94:95], v[94:95], v[236:237] op_sel_hi:[1,0]
	v_pk_mul_f32 v[84:85], v[84:85], v[236:237] op_sel_hi:[1,0]
	v_pk_mul_f32 v[86:87], v[86:87], v[236:237] op_sel_hi:[1,0]
	v_pk_mul_f32 v[76:77], v[76:77], v[238:239] op_sel_hi:[1,0]
; __device__ __forceinline__ unsigned cvt_pk_bf16(float lo, float hi) { unsigned r; asm volatile("v_cvt_pk_bf16_f32 %0, %1, %2" : "=v"(r) : "v"(lo), "v"(hi)); return r; }
; __device__ __forceinline__ float sigmoidf_(float x) { return fast_rcp(1.0f + fast_exp2(-1.4426950408889634f * x)); }
;     __device__ __forceinline__ void operator()(const f32x4 (&acc)[2][2][4][2], const Unit& u, int wr, int wc, int fr, int fq) const {
;     ...
;             for (int m = 0; m < 4; ++m) { const float sc = rs[ai][m]; f32x4 o[2];
; #pragma unroll
;                 for (int n = 0; n < 2; ++n) { const f32x4 g = acc[ai][0][m][n] * sc, up = acc[ai][1][m][n] * sc;
; #pragma unroll
;                     for (int e = 0; e < 4; ++e) o[n][e] = g[e] * sigmoidf_(g[e]) * up[e]; }
;                 u32x4 w; w.x = cvt_pk_bf16(o[0][0], o[0][1]); w.y = cvt_pk_bf16(o[0][2], o[0][3]); w.z = cvt_pk_bf16(o[1][0], o[1][1]); w.w = cvt_pk_bf16(o[1][2], o[1][3]);
;                 *(u32x4*)(O + (size_t)(row0 + ai * HALF + m * 16) * FF + col0) = w; }
	v_pk_mul_f32 v[78:79], v[78:79], v[238:239] op_sel_hi:[1,0]
	v_pk_mul_f32 v[68:69], v[68:69], v[238:239] op_sel_hi:[1,0]
	v_pk_mul_f32 v[70:71], v[70:71], v[238:239] op_sel_hi:[1,0]
	v_pk_mul_f32 v[128:129], v[92:93], v[248:249] op_sel_hi:[1,0]
	v_pk_mul_f32 v[130:131], v[94:95], v[248:249] op_sel_hi:[1,0]
	v_pk_mul_f32 v[132:133], v[84:85], v[248:249] op_sel_hi:[1,0]
	v_pk_mul_f32 v[134:135], v[86:87], v[248:249] op_sel_hi:[1,0]
	v_pk_mul_f32 v[162:163], v[76:77], v[248:249] op_sel_hi:[1,0]
	v_pk_mul_f32 v[164:165], v[78:79], v[248:249] op_sel_hi:[1,0]
	v_pk_mul_f32 v[166:167], v[68:69], v[248:249] op_sel_hi:[1,0]
	v_pk_mul_f32 v[168:169], v[70:71], v[248:249] op_sel_hi:[1,0]
	v_exp_f32_e32 v128, v128
	v_exp_f32_e32 v129, v129
	v_exp_f32_e32 v130, v130
	v_exp_f32_e32 v131, v131
	v_exp_f32_e32 v132, v132
	v_exp_f32_e32 v133, v133
	v_exp_f32_e32 v134, v134
	v_exp_f32_e32 v135, v135
	v_exp_f32_e32 v162, v162
	v_exp_f32_e32 v163, v163
	v_exp_f32_e32 v164, v164
	v_exp_f32_e32 v165, v165
	v_exp_f32_e32 v166, v166
	v_exp_f32_e32 v167, v167
	v_exp_f32_e32 v168, v168
	v_exp_f32_e32 v169, v169
	v_pk_mul_f32 v[88:89], v[88:89], v[236:237] op_sel_hi:[1,0]
	v_pk_mul_f32 v[90:91], v[90:91], v[236:237] op_sel_hi:[1,0]
	v_pk_mul_f32 v[80:81], v[80:81], v[236:237] op_sel_hi:[1,0]
	v_pk_mul_f32 v[82:83], v[82:83], v[236:237] op_sel_hi:[1,0]
	v_pk_mul_f32 v[72:73], v[72:73], v[238:239] op_sel_hi:[1,0]
	v_pk_mul_f32 v[74:75], v[74:75], v[238:239] op_sel_hi:[1,0]
	v_pk_mul_f32 v[64:65], v[64:65], v[238:239] op_sel_hi:[1,0]
	v_pk_mul_f32 v[66:67], v[66:67], v[238:239] op_sel_hi:[1,0]
	v_pk_add_f32 v[128:129], v[128:129], 1.0 op_sel_hi:[1,0]
	v_pk_add_f32 v[130:131], v[130:131], 1.0 op_sel_hi:[1,0]
	v_pk_add_f32 v[132:133], v[132:133], 1.0 op_sel_hi:[1,0]
	v_pk_add_f32 v[134:135], v[134:135], 1.0 op_sel_hi:[1,0]
	v_pk_add_f32 v[162:163], v[162:163], 1.0 op_sel_hi:[1,0]
	v_pk_add_f32 v[164:165], v[164:165], 1.0 op_sel_hi:[1,0]
	v_pk_add_f32 v[166:167], v[166:167], 1.0 op_sel_hi:[1,0]
	v_pk_add_f32 v[168:169], v[168:169], 1.0 op_sel_hi:[1,0]
	v_rcp_f32_e32 v128, v128
	v_rcp_f32_e32 v129, v129
	v_rcp_f32_e32 v130, v130
	v_rcp_f32_e32 v131, v131
	v_rcp_f32_e32 v132, v132
	v_rcp_f32_e32 v133, v133
	v_rcp_f32_e32 v134, v134
	v_rcp_f32_e32 v135, v135
	v_rcp_f32_e32 v162, v162
	v_rcp_f32_e32 v163, v163
	v_rcp_f32_e32 v164, v164
	v_rcp_f32_e32 v165, v165
	v_rcp_f32_e32 v166, v166
	v_rcp_f32_e32 v167, v167
	v_rcp_f32_e32 v168, v168
	v_rcp_f32_e32 v169, v169
	v_add_u32_e32 v140, 0x58000, v251
	v_add_u32_e32 v174, 0x84000, v251
	v_pk_mul_f32 v[92:93], v[92:93], v[128:129]
	v_pk_mul_f32 v[94:95], v[94:95], v[130:131]
	v_pk_mul_f32 v[84:85], v[84:85], v[132:133]
	v_pk_mul_f32 v[86:87], v[86:87], v[134:135]
	v_pk_mul_f32 v[76:77], v[76:77], v[162:163]
	v_pk_mul_f32 v[78:79], v[78:79], v[164:165]
	v_pk_mul_f32 v[68:69], v[68:69], v[166:167]
	v_pk_mul_f32 v[70:71], v[70:71], v[168:169]
	v_pk_mul_f32 v[92:93], v[92:93], v[88:89]
	v_pk_mul_f32 v[94:95], v[94:95], v[90:91]
	v_pk_mul_f32 v[84:85], v[84:85], v[80:81]
	v_pk_mul_f32 v[86:87], v[86:87], v[82:83]
	v_pk_mul_f32 v[76:77], v[76:77], v[72:73]
	v_pk_mul_f32 v[78:79], v[78:79], v[74:75]
	v_pk_mul_f32 v[68:69], v[68:69], v[64:65]
	v_pk_mul_f32 v[70:71], v[70:71], v[66:67]
	v_cvt_pk_bf16_f32 v136, v92, v93
	v_cvt_pk_bf16_f32 v137, v94, v95
	v_cvt_pk_bf16_f32 v138, v84, v85
	v_cvt_pk_bf16_f32 v139, v86, v87
	v_cvt_pk_bf16_f32 v170, v76, v77
	v_cvt_pk_bf16_f32 v171, v78, v79
	v_cvt_pk_bf16_f32 v172, v68, v69
	v_cvt_pk_bf16_f32 v173, v70, v71
	global_store_dwordx4 v140, v[136:139], s[28:29]
	global_store_dwordx4 v174, v[170:173], s[28:29]
	s_nop 1
	v_pk_mul_f32 v[60:61], v[60:61], v[240:241] op_sel_hi:[1,0]
	v_pk_mul_f32 v[62:63], v[62:63], v[240:241] op_sel_hi:[1,0]
	v_pk_mul_f32 v[52:53], v[52:53], v[240:241] op_sel_hi:[1,0]
	v_pk_mul_f32 v[54:55], v[54:55], v[240:241] op_sel_hi:[1,0]
	v_pk_mul_f32 v[44:45], v[44:45], v[242:243] op_sel_hi:[1,0]
	v_pk_mul_f32 v[46:47], v[46:47], v[242:243] op_sel_hi:[1,0]
	v_pk_mul_f32 v[36:37], v[36:37], v[242:243] op_sel_hi:[1,0]
	v_pk_mul_f32 v[38:39], v[38:39], v[242:243] op_sel_hi:[1,0]
	v_pk_mul_f32 v[128:129], v[60:61], v[248:249] op_sel_hi:[1,0]
	v_pk_mul_f32 v[130:131], v[62:63], v[248:249] op_sel_hi:[1,0]
	v_pk_mul_f32 v[132:133], v[52:53], v[248:249] op_sel_hi:[1,0]
	v_pk_mul_f32 v[134:135], v[54:55], v[248:249] op_sel_hi:[1,0]
	v_pk_mul_f32 v[162:163], v[44:45], v[248:249] op_sel_hi:[1,0]
	v_pk_mul_f32 v[164:165], v[46:47], v[248:249] op_sel_hi:[1,0]
	v_pk_mul_f32 v[166:167], v[36:37], v[248:249] op_sel_hi:[1,0]
	v_pk_mul_f32 v[168:169], v[38:39], v[248:249] op_sel_hi:[1,0]
	v_exp_f32_e32 v128, v128
	v_exp_f32_e32 v129, v129
	v_exp_f32_e32 v130, v130
	v_exp_f32_e32 v131, v131
	v_exp_f32_e32 v132, v132
	v_exp_f32_e32 v133, v133
	v_exp_f32_e32 v134, v134
	v_exp_f32_e32 v135, v135
	v_exp_f32_e32 v162, v162
	v_exp_f32_e32 v163, v163
	v_exp_f32_e32 v164, v164
	v_exp_f32_e32 v165, v165
	v_exp_f32_e32 v166, v166
	v_exp_f32_e32 v167, v167
	v_exp_f32_e32 v168, v168
	v_exp_f32_e32 v169, v169
	v_pk_mul_f32 v[56:57], v[56:57], v[240:241] op_sel_hi:[1,0]
	v_pk_mul_f32 v[58:59], v[58:59], v[240:241] op_sel_hi:[1,0]
	v_pk_mul_f32 v[48:49], v[48:49], v[240:241] op_sel_hi:[1,0]
	v_pk_mul_f32 v[50:51], v[50:51], v[240:241] op_sel_hi:[1,0]
	v_pk_mul_f32 v[40:41], v[40:41], v[242:243] op_sel_hi:[1,0]
	v_pk_mul_f32 v[42:43], v[42:43], v[242:243] op_sel_hi:[1,0]
	v_pk_mul_f32 v[32:33], v[32:33], v[242:243] op_sel_hi:[1,0]
	v_pk_mul_f32 v[34:35], v[34:35], v[242:243] op_sel_hi:[1,0]
	v_pk_add_f32 v[128:129], v[128:129], 1.0 op_sel_hi:[1,0]
	v_pk_add_f32 v[130:131], v[130:131], 1.0 op_sel_hi:[1,0]
; __device__ __forceinline__ unsigned cvt_pk_bf16(float lo, float hi) { unsigned r; asm volatile("v_cvt_pk_bf16_f32 %0, %1, %2" : "=v"(r) : "v"(lo), "v"(hi)); return r; }
; __device__ __forceinline__ float sigmoidf_(float x) { return fast_rcp(1.0f + fast_exp2(-1.4426950408889634f * x)); }
; __device__ __forceinline__ void load_rstd(const float* part, int row0, int fq, float (&rs)[2][4]) {
;     ...
;         for (int m = 0; m < 4; ++m) { const float* p = part + (size_t)(row0 + ai * HALF + m * 16) * NPART + fq * 8;
;             const f32x4 a = *(const f32x4*)p, b = *(const f32x4*)(p + 4); float s = ((a[0] + a[1]) + (a[2] + a[3])) + ((b[0] + b[1]) + (b[2] + b[3]));
;             s += __shfl_xor(s, 16); s += __shfl_xor(s, 32); rs[ai][m] = rsqrtf(s * (1.0f / D) + RMS_EPS); }
;     __device__ __forceinline__ void operator()(const f32x4 (&acc)[2][2][4][2], const Unit& u, int wr, int wc, int fr, int fq) const {
;     ...
;             for (int m = 0; m < 4; ++m) { const float sc = rs[ai][m]; f32x4 o[2];
; #pragma unroll
;                 for (int n = 0; n < 2; ++n) { const f32x4 g = acc[ai][0][m][n] * sc, up = acc[ai][1][m][n] * sc;
; #pragma unroll
;                     for (int e = 0; e < 4; ++e) o[n][e] = g[e] * sigmoidf_(g[e]) * up[e]; }
;                 u32x4 w; w.x = cvt_pk_bf16(o[0][0], o[0][1]); w.y = cvt_pk_bf16(o[0][2], o[0][3]); w.z = cvt_pk_bf16(o[1][0], o[1][1]); w.w = cvt_pk_bf16(o[1][2], o[1][3]);
;                 *(u32x4*)(O + (size_t)(row0 + ai * HALF + m * 16) * FF + col0) = w; }
	v_pk_add_f32 v[132:133], v[132:133], 1.0 op_sel_hi:[1,0]
	v_pk_add_f32 v[134:135], v[134:135], 1.0 op_sel_hi:[1,0]
	v_pk_add_f32 v[162:163], v[162:163], 1.0 op_sel_hi:[1,0]
	v_pk_add_f32 v[164:165], v[164:165], 1.0 op_sel_hi:[1,0]
	v_pk_add_f32 v[166:167], v[166:167], 1.0 op_sel_hi:[1,0]
	v_pk_add_f32 v[168:169], v[168:169], 1.0 op_sel_hi:[1,0]
	v_rcp_f32_e32 v128, v128
	v_rcp_f32_e32 v129, v129
	v_rcp_f32_e32 v130, v130
	v_rcp_f32_e32 v131, v131
	v_rcp_f32_e32 v132, v132
	v_rcp_f32_e32 v133, v133
	v_rcp_f32_e32 v134, v134
	v_rcp_f32_e32 v135, v135
	v_rcp_f32_e32 v162, v162
	v_rcp_f32_e32 v163, v163
	v_rcp_f32_e32 v164, v164
	v_rcp_f32_e32 v165, v165
	v_rcp_f32_e32 v166, v166
	v_rcp_f32_e32 v167, v167
	v_rcp_f32_e32 v168, v168
	v_rcp_f32_e32 v169, v169
	v_add_u32_e32 v140, 0x160000, v251
	v_add_u32_e32 v174, 0x18c000, v251
	v_pk_mul_f32 v[60:61], v[60:61], v[128:129]
	v_pk_mul_f32 v[62:63], v[62:63], v[130:131]
	v_pk_mul_f32 v[52:53], v[52:53], v[132:133]
	v_pk_mul_f32 v[54:55], v[54:55], v[134:135]
	v_pk_mul_f32 v[44:45], v[44:45], v[162:163]
	v_pk_mul_f32 v[46:47], v[46:47], v[164:165]
	v_pk_mul_f32 v[36:37], v[36:37], v[166:167]
	v_pk_mul_f32 v[38:39], v[38:39], v[168:169]
	v_pk_mul_f32 v[60:61], v[60:61], v[56:57]
	v_pk_mul_f32 v[62:63], v[62:63], v[58:59]
	v_pk_mul_f32 v[52:53], v[52:53], v[48:49]
	v_pk_mul_f32 v[54:55], v[54:55], v[50:51]
	v_pk_mul_f32 v[44:45], v[44:45], v[40:41]
	v_pk_mul_f32 v[46:47], v[46:47], v[42:43]
	v_pk_mul_f32 v[36:37], v[36:37], v[32:33]
	v_pk_mul_f32 v[38:39], v[38:39], v[34:35]
	v_cvt_pk_bf16_f32 v136, v60, v61
	v_cvt_pk_bf16_f32 v137, v62, v63
	v_cvt_pk_bf16_f32 v138, v52, v53
	v_cvt_pk_bf16_f32 v139, v54, v55
	v_cvt_pk_bf16_f32 v170, v44, v45
	v_cvt_pk_bf16_f32 v171, v46, v47
	v_cvt_pk_bf16_f32 v172, v36, v37
	v_cvt_pk_bf16_f32 v173, v38, v39
	global_store_dwordx4 v140, v[136:139], s[28:29]
	global_store_dwordx4 v174, v[170:173], s[28:29]
	s_nop 1
	v_pk_mul_f32 v[28:29], v[28:29], v[244:245] op_sel_hi:[1,0]
	v_pk_mul_f32 v[30:31], v[30:31], v[244:245] op_sel_hi:[1,0]
	v_pk_mul_f32 v[20:21], v[20:21], v[244:245] op_sel_hi:[1,0]
	v_pk_mul_f32 v[22:23], v[22:23], v[244:245] op_sel_hi:[1,0]
	v_pk_mul_f32 v[12:13], v[12:13], v[246:247] op_sel_hi:[1,0]
	v_pk_mul_f32 v[14:15], v[14:15], v[246:247] op_sel_hi:[1,0]
	v_pk_mul_f32 v[4:5], v[4:5], v[246:247] op_sel_hi:[1,0]
	v_pk_mul_f32 v[6:7], v[6:7], v[246:247] op_sel_hi:[1,0]
	v_pk_mul_f32 v[128:129], v[28:29], v[248:249] op_sel_hi:[1,0]
	v_pk_mul_f32 v[130:131], v[30:31], v[248:249] op_sel_hi:[1,0]
	v_pk_mul_f32 v[132:133], v[20:21], v[248:249] op_sel_hi:[1,0]
	v_pk_mul_f32 v[134:135], v[22:23], v[248:249] op_sel_hi:[1,0]
	v_pk_mul_f32 v[162:163], v[12:13], v[248:249] op_sel_hi:[1,0]
	v_pk_mul_f32 v[164:165], v[14:15], v[248:249] op_sel_hi:[1,0]
	v_pk_mul_f32 v[166:167], v[4:5], v[248:249] op_sel_hi:[1,0]
	v_pk_mul_f32 v[168:169], v[6:7], v[248:249] op_sel_hi:[1,0]
	v_exp_f32_e32 v128, v128
	v_exp_f32_e32 v129, v129
	v_exp_f32_e32 v130, v130
	v_exp_f32_e32 v131, v131
	v_exp_f32_e32 v132, v132
	v_exp_f32_e32 v133, v133
	v_exp_f32_e32 v134, v134
	v_exp_f32_e32 v135, v135
	v_exp_f32_e32 v162, v162
	v_exp_f32_e32 v163, v163
	v_exp_f32_e32 v164, v164
	v_exp_f32_e32 v165, v165
	v_exp_f32_e32 v166, v166
	v_exp_f32_e32 v167, v167
	v_exp_f32_e32 v168, v168
	v_exp_f32_e32 v169, v169
	v_pk_mul_f32 v[24:25], v[24:25], v[244:245] op_sel_hi:[1,0]
	v_pk_mul_f32 v[26:27], v[26:27], v[244:245] op_sel_hi:[1,0]
	v_pk_mul_f32 v[16:17], v[16:17], v[244:245] op_sel_hi:[1,0]
	v_pk_mul_f32 v[18:19], v[18:19], v[244:245] op_sel_hi:[1,0]
	v_pk_mul_f32 v[8:9], v[8:9], v[246:247] op_sel_hi:[1,0]
	v_pk_mul_f32 v[10:11], v[10:11], v[246:247] op_sel_hi:[1,0]
	v_pk_mul_f32 v[0:1], v[0:1], v[246:247] op_sel_hi:[1,0]
	v_pk_mul_f32 v[2:3], v[2:3], v[246:247] op_sel_hi:[1,0]
	v_pk_add_f32 v[128:129], v[128:129], 1.0 op_sel_hi:[1,0]
	v_pk_add_f32 v[130:131], v[130:131], 1.0 op_sel_hi:[1,0]
	v_pk_add_f32 v[132:133], v[132:133], 1.0 op_sel_hi:[1,0]
	v_pk_add_f32 v[134:135], v[134:135], 1.0 op_sel_hi:[1,0]
	v_pk_add_f32 v[162:163], v[162:163], 1.0 op_sel_hi:[1,0]
	v_pk_add_f32 v[164:165], v[164:165], 1.0 op_sel_hi:[1,0]
	v_pk_add_f32 v[166:167], v[166:167], 1.0 op_sel_hi:[1,0]
	v_pk_add_f32 v[168:169], v[168:169], 1.0 op_sel_hi:[1,0]
	v_rcp_f32_e32 v128, v128
	v_rcp_f32_e32 v129, v129
	v_rcp_f32_e32 v130, v130
	v_rcp_f32_e32 v131, v131
	v_rcp_f32_e32 v132, v132
	v_rcp_f32_e32 v133, v133
	v_rcp_f32_e32 v134, v134
	v_rcp_f32_e32 v135, v135
	v_rcp_f32_e32 v162, v162
	v_rcp_f32_e32 v163, v163
	v_rcp_f32_e32 v164, v164
	v_rcp_f32_e32 v165, v165
	v_rcp_f32_e32 v166, v166
	v_rcp_f32_e32 v167, v167
	v_rcp_f32_e32 v168, v168
	v_rcp_f32_e32 v169, v169
	v_add_u32_e32 v140, 0x1b8000, v251
	v_add_u32_e32 v174, 0x1e4000, v251
	v_pk_mul_f32 v[28:29], v[28:29], v[128:129]
	v_pk_mul_f32 v[30:31], v[30:31], v[130:131]
	v_pk_mul_f32 v[20:21], v[20:21], v[132:133]
	v_pk_mul_f32 v[22:23], v[22:23], v[134:135]
	v_pk_mul_f32 v[12:13], v[12:13], v[162:163]
	v_pk_mul_f32 v[14:15], v[14:15], v[164:165]
	v_pk_mul_f32 v[4:5], v[4:5], v[166:167]
	v_pk_mul_f32 v[6:7], v[6:7], v[168:169]
	v_pk_mul_f32 v[28:29], v[28:29], v[24:25]
	v_pk_mul_f32 v[30:31], v[30:31], v[26:27]
	v_pk_mul_f32 v[20:21], v[20:21], v[16:17]
	v_pk_mul_f32 v[22:23], v[22:23], v[18:19]
	v_pk_mul_f32 v[12:13], v[12:13], v[8:9]
	v_pk_mul_f32 v[14:15], v[14:15], v[10:11]
	v_pk_mul_f32 v[4:5], v[4:5], v[0:1]
	v_pk_mul_f32 v[6:7], v[6:7], v[2:3]
	v_cvt_pk_bf16_f32 v136, v28, v29
	v_cvt_pk_bf16_f32 v137, v30, v31
	v_cvt_pk_bf16_f32 v138, v20, v21
	v_cvt_pk_bf16_f32 v139, v22, v23
	v_cvt_pk_bf16_f32 v170, v12, v13
	v_cvt_pk_bf16_f32 v171, v14, v15
	v_cvt_pk_bf16_f32 v172, v4, v5
	v_cvt_pk_bf16_f32 v173, v6, v7
	global_store_dwordx4 v140, v[136:139], s[28:29]
	global_store_dwordx4 v174, v[170:173], s[28:29]
	s_cmp_lg_u64 s[2:3], 0
	s_cbranch_scc0 .Lswg_nf_SWG_LBB0_264
	s_waitcnt vmcnt(8)
	v_add_f32_e32 v200, v200, v201
	v_add_f32_e32 v202, v202, v203
	v_add_f32_e32 v204, v204, v205
	v_add_f32_e32 v206, v206, v207
	v_add_f32_e32 v208, v208, v209
	v_add_f32_e32 v210, v210, v211
	v_add_f32_e32 v212, v212, v213
	v_add_f32_e32 v214, v214, v215
	v_add_f32_e32 v200, v200, v202
	v_add_f32_e32 v204, v204, v206
	v_add_f32_e32 v208, v208, v210
	v_add_f32_e32 v212, v212, v214
	v_add_f32_e32 v200, v200, v204
	v_add_f32_e32 v208, v208, v212
	v_add_f32_e32 v200, v200, v208
	s_nop 1
	v_add_f32_dpp v204, v200, v200 quad_perm:[1,0,3,2] row_mask:0xf bank_mask:0xf
	v_fmamk_f32 v204, v204, 0x3a000000, v250
	v_rsq_f32_e32 v204, v204
	s_and_b32 s96, s99, 1
	s_xor_b32 s96, s96, 1
	s_lshl_b32 s96, s96, 10
	s_lshl_b32 s97, s95, 7
	s_add_i32 s96, s96, s97
	s_add_i32 s96, s96, 0x21000
	v_lshrrev_b32_e32 v216, 1, v220
	v_lshl_add_u32 v216, v216, 2, s96
	ds_write_b32 v216, v204
	s_and_b32 s99, s99, 1
	s_xor_b32 s99, s99, 3
	s_branch .Lswg_end_SWG_LBB0_264
; #define PG8_BAR __builtin_amdgcn_s_barrier()
; template <class Epi, class Sched, bool ALIGN_EPI>
; __device__ __forceinline__ void gemm_phase(LAS unsigned char* lds, const Gemm g, const Sched& S, const Epi& E) {
;     ...
;         if (!has_next) break;
; #pragma unroll
;         for (int a = 0; a < 2; ++a)
; #pragma unroll
;             for (int b = 0; b < 2; ++b)
; #pragma unroll
;                 for (int m = 0; m < 4; ++m)
; #pragma unroll
;                     for (int n = 0; n < 2; ++n) acc[a][b][m][n] = (f32x4){0.f, 0.f, 0.f, 0.f};
;         cur = nxt; cA = nA; cB = nB; ++ui;
;         if constexpr (ALIGN_EPI) { if (wr == 1) PG8_BAR; }
.Lswg_nf_SWG_LBB0_264:
	s_mov_b32 s99, 0
.Lswg_end_SWG_LBB0_264:
	s_andn2_b64 vcc, exec, s[2:3]
	s_mov_b64 s[2:3], -1
	s_cbranch_vccnz .LBB0_257
	s_andn2_b64 vcc, exec, s[26:27]
	s_cbranch_vccnz .LBB0_256
	s_barrier
	s_branch .LBB0_256

; __device__ __forceinline__ void load_rstd(const float* part, int row0, int fq, float (&rs)[2][4]) {
; #pragma unroll
;     for (int ai = 0; ai < 2; ++ai)
; #pragma unroll
;         for (int m = 0; m < 4; ++m) { const float* p = part + (size_t)(row0 + ai * HALF + m * 16) * NPART + fq * 8;
;             const f32x4 a = *(const f32x4*)p, b = *(const f32x4*)(p + 4); float s = ((a[0] + a[1]) + (a[2] + a[3])) + ((b[0] + b[1]) + (b[2] + b[3]));
;             s += __shfl_xor(s, 16); s += __shfl_xor(s, 32); rs[ai][m] = rsqrtf(s * (1.0f / D) + RMS_EPS); }
.LBB0_1151:
	s_bitcmp1_b32 s99, 1
	s_cbranch_scc1 .Lswg_rs_SWG_LBB0_1151
	v_lshl_add_u32 v237, s11, 8, v181
	s_mov_b64 vcc, 0x1000
	s_mov_b64 s[100:101], 0x4000
	v_ashrrev_i32_e32 v179, 31, v237
	v_mov_b32_e32 v178, v237
	v_lshlrev_b64 v[178:179], 7, v[178:179]
	v_lshl_add_u64 v[178:179], v[152:153], 0, v[178:179]
	v_lshl_add_u64 v[222:223], v[178:179], 0, vcc
	v_lshl_add_u64 v[224:225], v[178:179], 0, s[100:101]
	v_lshl_add_u64 v[226:227], v[224:225], 0, vcc
	global_load_dwordx4 v[128:131], v[178:179], off
	global_load_dwordx4 v[132:135], v[178:179], off offset:16
	global_load_dwordx4 v[136:139], v[178:179], off offset:2048
	global_load_dwordx4 v[140:143], v[178:179], off offset:2064
	global_load_dwordx4 v[162:165], v[222:223], off
	global_load_dwordx4 v[166:169], v[222:223], off offset:16
	global_load_dwordx4 v[170:173], v[222:223], off offset:2048
	global_load_dwordx4 v[174:177], v[222:223], off offset:2064
	global_load_dwordx4 v[188:191], v[224:225], off
	global_load_dwordx4 v[192:195], v[224:225], off offset:16
	global_load_dwordx4 v[196:199], v[224:225], off offset:2048
	global_load_dwordx4 v[200:203], v[224:225], off offset:2064
	global_load_dwordx4 v[204:207], v[226:227], off
	global_load_dwordx4 v[208:211], v[226:227], off offset:16
	global_load_dwordx4 v[212:215], v[226:227], off offset:2048
	global_load_dwordx4 v[216:219], v[226:227], off offset:2064
	v_mov_b32_e32 v236, 0xbfb8aa3b
	v_mov_b32_e32 v238, 0x358637bd
	v_lshl_or_b32 v239, s73, 7, v183
	v_lshlrev_b32_e32 v239, 1, v239
	v_mul_u32_u24_e32 v237, 0x2c00, v237
	v_add_u32_e32 v239, v239, v237
	s_waitcnt vmcnt(0)
	v_add_f32_e32 v128, v128, v129
	v_add_f32_e32 v130, v130, v131
	v_add_f32_e32 v132, v132, v133
	v_add_f32_e32 v134, v134, v135
	v_add_f32_e32 v136, v136, v137
	v_add_f32_e32 v138, v138, v139
	v_add_f32_e32 v140, v140, v141
	v_add_f32_e32 v142, v142, v143
	v_add_f32_e32 v162, v162, v163
	v_add_f32_e32 v164, v164, v165
	v_add_f32_e32 v166, v166, v167
	v_add_f32_e32 v168, v168, v169
	v_add_f32_e32 v170, v170, v171
	v_add_f32_e32 v172, v172, v173
	v_add_f32_e32 v174, v174, v175
	v_add_f32_e32 v176, v176, v177
	v_add_f32_e32 v188, v188, v189
	v_add_f32_e32 v190, v190, v191
	v_add_f32_e32 v192, v192, v193
	v_add_f32_e32 v194, v194, v195
	v_add_f32_e32 v196, v196, v197
	v_add_f32_e32 v198, v198, v199
	v_add_f32_e32 v200, v200, v201
	v_add_f32_e32 v202, v202, v203
	v_add_f32_e32 v204, v204, v205
	v_add_f32_e32 v206, v206, v207
	v_add_f32_e32 v208, v208, v209
	v_add_f32_e32 v210, v210, v211
	v_add_f32_e32 v212, v212, v213
	v_add_f32_e32 v214, v214, v215
	v_add_f32_e32 v216, v216, v217
	v_add_f32_e32 v218, v218, v219
	v_add_f32_e32 v128, v128, v130
	v_add_f32_e32 v132, v132, v134
	v_add_f32_e32 v136, v136, v138
	v_add_f32_e32 v140, v140, v142
	v_add_f32_e32 v162, v162, v164
	v_add_f32_e32 v166, v166, v168
	v_add_f32_e32 v170, v170, v172
	v_add_f32_e32 v174, v174, v176
	v_add_f32_e32 v188, v188, v190
	v_add_f32_e32 v192, v192, v194
	v_add_f32_e32 v196, v196, v198
	v_add_f32_e32 v200, v200, v202
	v_add_f32_e32 v204, v204, v206
	v_add_f32_e32 v208, v208, v210
	v_add_f32_e32 v212, v212, v214
	v_add_f32_e32 v216, v216, v218
	v_add_f32_e32 v128, v128, v132
	v_add_f32_e32 v136, v136, v140
	v_add_f32_e32 v162, v162, v166
	v_add_f32_e32 v170, v170, v174
	v_add_f32_e32 v188, v188, v192
	v_add_f32_e32 v196, v196, v200
	v_add_f32_e32 v204, v204, v208
	v_add_f32_e32 v212, v212, v216
	v_mov_b32_e32 v179, v128
	v_mov_b32_e32 v223, v136
	v_mov_b32_e32 v225, v162
	v_mov_b32_e32 v227, v170
	v_mov_b32_e32 v229, v188
	v_mov_b32_e32 v231, v196
	v_mov_b32_e32 v233, v204
	v_mov_b32_e32 v235, v212
	s_nop 1
	v_permlane16_swap_b32_e32 v128, v179
	v_permlane16_swap_b32_e32 v136, v223
	v_permlane16_swap_b32_e32 v162, v225
	v_permlane16_swap_b32_e32 v170, v227
	v_permlane16_swap_b32_e32 v188, v229
	v_permlane16_swap_b32_e32 v196, v231
	v_permlane16_swap_b32_e32 v204, v233
	v_permlane16_swap_b32_e32 v212, v235
	v_add_f32_e32 v128, v128, v179
	v_add_f32_e32 v136, v136, v223
	v_add_f32_e32 v162, v162, v225
	v_add_f32_e32 v170, v170, v227
	v_add_f32_e32 v188, v188, v229
	v_add_f32_e32 v196, v196, v231
	v_add_f32_e32 v204, v204, v233
	v_add_f32_e32 v212, v212, v235
	v_mov_b32_e32 v179, v128
	v_mov_b32_e32 v223, v136
	v_mov_b32_e32 v225, v162
	v_mov_b32_e32 v227, v170
	v_mov_b32_e32 v229, v188
	v_mov_b32_e32 v231, v196
	v_mov_b32_e32 v233, v204
	v_mov_b32_e32 v235, v212
	s_nop 1
	v_permlane32_swap_b32_e32 v128, v179
	v_permlane32_swap_b32_e32 v136, v223
	v_permlane32_swap_b32_e32 v162, v225
	v_permlane32_swap_b32_e32 v170, v227
	v_permlane32_swap_b32_e32 v188, v229
	v_permlane32_swap_b32_e32 v196, v231
	v_permlane32_swap_b32_e32 v204, v233
	v_permlane32_swap_b32_e32 v212, v235
	v_add_f32_e32 v128, v128, v179
	v_add_f32_e32 v136, v136, v223
	v_add_f32_e32 v162, v162, v225
	v_add_f32_e32 v170, v170, v227
	v_add_f32_e32 v188, v188, v229
	v_add_f32_e32 v196, v196, v231
	v_add_f32_e32 v204, v204, v233
	v_add_f32_e32 v212, v212, v235
	v_fmamk_f32 v178, v128, 0x3a000000, v238
	v_fmamk_f32 v222, v136, 0x3a000000, v238
	v_fmamk_f32 v224, v162, 0x3a000000, v238
	v_fmamk_f32 v226, v170, 0x3a000000, v238
	v_fmamk_f32 v228, v188, 0x3a000000, v238
	v_fmamk_f32 v230, v196, 0x3a000000, v238
	v_fmamk_f32 v232, v204, 0x3a000000, v238
	v_fmamk_f32 v234, v212, 0x3a000000, v238
	v_rsq_f32_e32 v178, v178
	v_rsq_f32_e32 v222, v222
	v_rsq_f32_e32 v224, v224
	v_rsq_f32_e32 v226, v226
	v_rsq_f32_e32 v228, v228
	v_rsq_f32_e32 v230, v230
	v_rsq_f32_e32 v232, v232
	v_rsq_f32_e32 v234, v234
	s_branch .Lswg_go_SWG_LBB0_1151
; __device__ __forceinline__ unsigned cvt_pk_bf16(float lo, float hi) { unsigned r; asm volatile("v_cvt_pk_bf16_f32 %0, %1, %2" : "=v"(r) : "v"(lo), "v"(hi)); return r; }
; __device__ __forceinline__ float sigmoidf_(float x) { return fast_rcp(1.0f + fast_exp2(-1.4426950408889634f * x)); }
; __device__ __forceinline__ void load_rstd(const float* part, int row0, int fq, float (&rs)[2][4]) {
; #pragma unroll
;     for (int ai = 0; ai < 2; ++ai)
; #pragma unroll
;         for (int m = 0; m < 4; ++m) { const float* p = part + (size_t)(row0 + ai * HALF + m * 16) * NPART + fq * 8;
;             const f32x4 a = *(const f32x4*)p, b = *(const f32x4*)(p + 4); float s = ((a[0] + a[1]) + (a[2] + a[3])) + ((b[0] + b[1]) + (b[2] + b[3]));
;             s += __shfl_xor(s, 16); s += __shfl_xor(s, 32); rs[ai][m] = rsqrtf(s * (1.0f / D) + RMS_EPS); }
;     __device__ __forceinline__ void operator()(const f32x4 (&acc)[2][2][4][2], const Unit& u, int wr, int wc, int fr, int fq) const {
;     ...
;             for (int m = 0; m < 4; ++m) { const float sc = rs[ai][m]; f32x4 o[2];
; #pragma unroll
;                 for (int n = 0; n < 2; ++n) { const f32x4 g = acc[ai][0][m][n] * sc, up = acc[ai][1][m][n] * sc;
; #pragma unroll
;                     for (int e = 0; e < 4; ++e) o[n][e] = g[e] * sigmoidf_(g[e]) * up[e]; }
;                 u32x4 w; w.x = cvt_pk_bf16(o[0][0], o[0][1]); w.y = cvt_pk_bf16(o[0][2], o[0][3]); w.z = cvt_pk_bf16(o[1][0], o[1][1]); w.w = cvt_pk_bf16(o[1][2], o[1][3]);
;                 *(u32x4*)(O + (size_t)(row0 + ai * HALF + m * 16) * FF + col0) = w; }
.Lswg_rs_SWG_LBB0_1151:
	v_lshl_add_u32 v237, s11, 8, v181
	v_mov_b32_e32 v236, 0xbfb8aa3b
	v_mov_b32_e32 v238, 0x358637bd
	v_lshl_or_b32 v239, s73, 7, v183
	v_lshlrev_b32_e32 v239, 1, v239
	v_mul_u32_u24_e32 v237, 0x2c00, v237
	v_add_u32_e32 v239, v239, v237
	s_and_b32 s96, s99, 1
	s_lshl_b32 s96, s96, 10
	s_add_i32 s96, s96, 0x21000
	v_lshl_add_u32 v216, v181, 2, s96
	ds_read_b32 v178, v216
	ds_read_b32 v222, v216 offset:64
	ds_read_b32 v224, v216 offset:128
	ds_read_b32 v226, v216 offset:192
	ds_read_b32 v228, v216 offset:512
	ds_read_b32 v230, v216 offset:576
	ds_read_b32 v232, v216 offset:640
	ds_read_b32 v234, v216 offset:704
	s_waitcnt lgkmcnt(0)
.Lswg_go_SWG_LBB0_1151:
	s_cmp_lg_u64 s[2:3], 0
	s_cbranch_scc0 .Lswg_np_SWG_LBB0_1151
	v_lshrrev_b32_e32 v204, 1, v220
	s_lshl_b32 s96, s72, 8
	s_lshl_b32 s97, s95, 5
	s_add_i32 s96, s96, s97
	v_add_u32_e32 v204, s96, v204
	v_and_b32_e32 v205, 1, v220
	v_lshlrev_b32_e32 v205, 6, v205
	v_lshl_add_u32 v204, v204, 7, v205
	s_add_u32 s96, s14, 0xc300000
	s_addc_u32 s97, s15, 0
	global_load_dwordx4 v[188:191], v204, s[96:97]
	global_load_dwordx4 v[192:195], v204, s[96:97] offset:16
	global_load_dwordx4 v[196:199], v204, s[96:97] offset:32
	global_load_dwordx4 v[200:203], v204, s[96:97] offset:48
.Lswg_np_SWG_LBB0_1151:
	v_pk_mul_f32 v[124:125], v[124:125], v[178:179] op_sel_hi:[1,0]
	v_pk_mul_f32 v[126:127], v[126:127], v[178:179] op_sel_hi:[1,0]
	v_pk_mul_f32 v[116:117], v[116:117], v[178:179] op_sel_hi:[1,0]
	v_pk_mul_f32 v[118:119], v[118:119], v[178:179] op_sel_hi:[1,0]
	v_pk_mul_f32 v[108:109], v[108:109], v[222:223] op_sel_hi:[1,0]
	v_pk_mul_f32 v[110:111], v[110:111], v[222:223] op_sel_hi:[1,0]
	v_pk_mul_f32 v[100:101], v[100:101], v[222:223] op_sel_hi:[1,0]
	v_pk_mul_f32 v[102:103], v[102:103], v[222:223] op_sel_hi:[1,0]
	v_pk_mul_f32 v[128:129], v[124:125], v[236:237] op_sel_hi:[1,0]
	v_pk_mul_f32 v[130:131], v[126:127], v[236:237] op_sel_hi:[1,0]
	v_pk_mul_f32 v[132:133], v[116:117], v[236:237] op_sel_hi:[1,0]
	v_pk_mul_f32 v[134:135], v[118:119], v[236:237] op_sel_hi:[1,0]
	v_pk_mul_f32 v[162:163], v[108:109], v[236:237] op_sel_hi:[1,0]
	v_pk_mul_f32 v[164:165], v[110:111], v[236:237] op_sel_hi:[1,0]
	v_pk_mul_f32 v[166:167], v[100:101], v[236:237] op_sel_hi:[1,0]
	v_pk_mul_f32 v[168:169], v[102:103], v[236:237] op_sel_hi:[1,0]
	v_exp_f32_e32 v128, v128
	v_exp_f32_e32 v129, v129
	v_exp_f32_e32 v130, v130
	v_exp_f32_e32 v131, v131
	v_exp_f32_e32 v132, v132
	v_exp_f32_e32 v133, v133
	v_exp_f32_e32 v134, v134
	v_exp_f32_e32 v135, v135
	v_exp_f32_e32 v162, v162
	v_exp_f32_e32 v163, v163
	v_exp_f32_e32 v164, v164
	v_exp_f32_e32 v165, v165
	v_exp_f32_e32 v166, v166
	v_exp_f32_e32 v167, v167
	v_exp_f32_e32 v168, v168
	v_exp_f32_e32 v169, v169
	v_pk_mul_f32 v[120:121], v[120:121], v[178:179] op_sel_hi:[1,0]
	v_pk_mul_f32 v[122:123], v[122:123], v[178:179] op_sel_hi:[1,0]
	v_pk_mul_f32 v[112:113], v[112:113], v[178:179] op_sel_hi:[1,0]
	v_pk_mul_f32 v[114:115], v[114:115], v[178:179] op_sel_hi:[1,0]
	v_pk_mul_f32 v[104:105], v[104:105], v[222:223] op_sel_hi:[1,0]
	v_pk_mul_f32 v[106:107], v[106:107], v[222:223] op_sel_hi:[1,0]
	v_pk_mul_f32 v[96:97], v[96:97], v[222:223] op_sel_hi:[1,0]
	v_pk_mul_f32 v[98:99], v[98:99], v[222:223] op_sel_hi:[1,0]
	v_pk_add_f32 v[128:129], v[128:129], 1.0 op_sel_hi:[1,0]
	v_pk_add_f32 v[130:131], v[130:131], 1.0 op_sel_hi:[1,0]
	v_pk_add_f32 v[132:133], v[132:133], 1.0 op_sel_hi:[1,0]
	v_pk_add_f32 v[134:135], v[134:135], 1.0 op_sel_hi:[1,0]
	v_pk_add_f32 v[162:163], v[162:163], 1.0 op_sel_hi:[1,0]
	v_pk_add_f32 v[164:165], v[164:165], 1.0 op_sel_hi:[1,0]
	v_pk_add_f32 v[166:167], v[166:167], 1.0 op_sel_hi:[1,0]
	v_pk_add_f32 v[168:169], v[168:169], 1.0 op_sel_hi:[1,0]
	v_rcp_f32_e32 v128, v128
	v_rcp_f32_e32 v129, v129
	v_rcp_f32_e32 v130, v130
	v_rcp_f32_e32 v131, v131
	v_rcp_f32_e32 v132, v132
	v_rcp_f32_e32 v133, v133
	v_rcp_f32_e32 v134, v134
	v_rcp_f32_e32 v135, v135
	v_rcp_f32_e32 v162, v162
	v_rcp_f32_e32 v163, v163
	v_rcp_f32_e32 v164, v164
	v_rcp_f32_e32 v165, v165
	v_rcp_f32_e32 v166, v166
	v_rcp_f32_e32 v167, v167
	v_rcp_f32_e32 v168, v168
	v_rcp_f32_e32 v169, v169
	v_mov_b32_e32 v140, v239
	v_add_u32_e32 v174, 0x2c000, v239
	v_pk_mul_f32 v[124:125], v[124:125], v[128:129]
	v_pk_mul_f32 v[126:127], v[126:127], v[130:131]
	v_pk_mul_f32 v[116:117], v[116:117], v[132:133]
	v_pk_mul_f32 v[118:119], v[118:119], v[134:135]
	v_pk_mul_f32 v[108:109], v[108:109], v[162:163]
	v_pk_mul_f32 v[110:111], v[110:111], v[164:165]
	v_pk_mul_f32 v[100:101], v[100:101], v[166:167]
	v_pk_mul_f32 v[102:103], v[102:103], v[168:169]
	v_pk_mul_f32 v[124:125], v[124:125], v[120:121]
	v_pk_mul_f32 v[126:127], v[126:127], v[122:123]
	v_pk_mul_f32 v[116:117], v[116:117], v[112:113]
	v_pk_mul_f32 v[118:119], v[118:119], v[114:115]
	v_pk_mul_f32 v[108:109], v[108:109], v[104:105]
	v_pk_mul_f32 v[110:111], v[110:111], v[106:107]
	v_pk_mul_f32 v[100:101], v[100:101], v[96:97]
	v_pk_mul_f32 v[102:103], v[102:103], v[98:99]
	v_cvt_pk_bf16_f32 v136, v124, v125
	v_cvt_pk_bf16_f32 v137, v126, v127
	v_cvt_pk_bf16_f32 v138, v116, v117
	v_cvt_pk_bf16_f32 v139, v118, v119
	v_cvt_pk_bf16_f32 v170, v108, v109
	v_cvt_pk_bf16_f32 v171, v110, v111
	v_cvt_pk_bf16_f32 v172, v100, v101
	v_cvt_pk_bf16_f32 v173, v102, v103
	global_store_dwordx4 v140, v[136:139], s[28:29]
	global_store_dwordx4 v174, v[170:173], s[28:29]
	s_nop 1
	v_pk_mul_f32 v[92:93], v[92:93], v[224:225] op_sel_hi:[1,0]
	v_pk_mul_f32 v[94:95], v[94:95], v[224:225] op_sel_hi:[1,0]
	v_pk_mul_f32 v[84:85], v[84:85], v[224:225] op_sel_hi:[1,0]
	v_pk_mul_f32 v[86:87], v[86:87], v[224:225] op_sel_hi:[1,0]
; __device__ __forceinline__ unsigned cvt_pk_bf16(float lo, float hi) { unsigned r; asm volatile("v_cvt_pk_bf16_f32 %0, %1, %2" : "=v"(r) : "v"(lo), "v"(hi)); return r; }
; __device__ __forceinline__ float sigmoidf_(float x) { return fast_rcp(1.0f + fast_exp2(-1.4426950408889634f * x)); }
;     __device__ __forceinline__ void operator()(const f32x4 (&acc)[2][2][4][2], const Unit& u, int wr, int wc, int fr, int fq) const {
;     ...
;             for (int m = 0; m < 4; ++m) { const float sc = rs[ai][m]; f32x4 o[2];
; #pragma unroll
;                 for (int n = 0; n < 2; ++n) { const f32x4 g = acc[ai][0][m][n] * sc, up = acc[ai][1][m][n] * sc;
; #pragma unroll
;                     for (int e = 0; e < 4; ++e) o[n][e] = g[e] * sigmoidf_(g[e]) * up[e]; }
;                 u32x4 w; w.x = cvt_pk_bf16(o[0][0], o[0][1]); w.y = cvt_pk_bf16(o[0][2], o[0][3]); w.z = cvt_pk_bf16(o[1][0], o[1][1]); w.w = cvt_pk_bf16(o[1][2], o[1][3]);
;                 *(u32x4*)(O + (size_t)(row0 + ai * HALF + m * 16) * FF + col0) = w; }
	v_pk_mul_f32 v[76:77], v[76:77], v[226:227] op_sel_hi:[1,0]
	v_pk_mul_f32 v[78:79], v[78:79], v[226:227] op_sel_hi:[1,0]
	v_pk_mul_f32 v[68:69], v[68:69], v[226:227] op_sel_hi:[1,0]
	v_pk_mul_f32 v[70:71], v[70:71], v[226:227] op_sel_hi:[1,0]
	v_pk_mul_f32 v[128:129], v[92:93], v[236:237] op_sel_hi:[1,0]
	v_pk_mul_f32 v[130:131], v[94:95], v[236:237] op_sel_hi:[1,0]
	v_pk_mul_f32 v[132:133], v[84:85], v[236:237] op_sel_hi:[1,0]
	v_pk_mul_f32 v[134:135], v[86:87], v[236:237] op_sel_hi:[1,0]
	v_pk_mul_f32 v[162:163], v[76:77], v[236:237] op_sel_hi:[1,0]
	v_pk_mul_f32 v[164:165], v[78:79], v[236:237] op_sel_hi:[1,0]
	v_pk_mul_f32 v[166:167], v[68:69], v[236:237] op_sel_hi:[1,0]
	v_pk_mul_f32 v[168:169], v[70:71], v[236:237] op_sel_hi:[1,0]
	v_exp_f32_e32 v128, v128
	v_exp_f32_e32 v129, v129
	v_exp_f32_e32 v130, v130
	v_exp_f32_e32 v131, v131
	v_exp_f32_e32 v132, v132
	v_exp_f32_e32 v133, v133
	v_exp_f32_e32 v134, v134
	v_exp_f32_e32 v135, v135
	v_exp_f32_e32 v162, v162
	v_exp_f32_e32 v163, v163
	v_exp_f32_e32 v164, v164
	v_exp_f32_e32 v165, v165
	v_exp_f32_e32 v166, v166
	v_exp_f32_e32 v167, v167
	v_exp_f32_e32 v168, v168
	v_exp_f32_e32 v169, v169
	v_pk_mul_f32 v[88:89], v[88:89], v[224:225] op_sel_hi:[1,0]
	v_pk_mul_f32 v[90:91], v[90:91], v[224:225] op_sel_hi:[1,0]
	v_pk_mul_f32 v[80:81], v[80:81], v[224:225] op_sel_hi:[1,0]
	v_pk_mul_f32 v[82:83], v[82:83], v[224:225] op_sel_hi:[1,0]
	v_pk_mul_f32 v[72:73], v[72:73], v[226:227] op_sel_hi:[1,0]
	v_pk_mul_f32 v[74:75], v[74:75], v[226:227] op_sel_hi:[1,0]
	v_pk_mul_f32 v[64:65], v[64:65], v[226:227] op_sel_hi:[1,0]
	v_pk_mul_f32 v[66:67], v[66:67], v[226:227] op_sel_hi:[1,0]
	v_pk_add_f32 v[128:129], v[128:129], 1.0 op_sel_hi:[1,0]
	v_pk_add_f32 v[130:131], v[130:131], 1.0 op_sel_hi:[1,0]
	v_pk_add_f32 v[132:133], v[132:133], 1.0 op_sel_hi:[1,0]
	v_pk_add_f32 v[134:135], v[134:135], 1.0 op_sel_hi:[1,0]
	v_pk_add_f32 v[162:163], v[162:163], 1.0 op_sel_hi:[1,0]
	v_pk_add_f32 v[164:165], v[164:165], 1.0 op_sel_hi:[1,0]
	v_pk_add_f32 v[166:167], v[166:167], 1.0 op_sel_hi:[1,0]
	v_pk_add_f32 v[168:169], v[168:169], 1.0 op_sel_hi:[1,0]
	v_rcp_f32_e32 v128, v128
	v_rcp_f32_e32 v129, v129
	v_rcp_f32_e32 v130, v130
	v_rcp_f32_e32 v131, v131
	v_rcp_f32_e32 v132, v132
	v_rcp_f32_e32 v133, v133
	v_rcp_f32_e32 v134, v134
	v_rcp_f32_e32 v135, v135
	v_rcp_f32_e32 v162, v162
	v_rcp_f32_e32 v163, v163
	v_rcp_f32_e32 v164, v164
	v_rcp_f32_e32 v165, v165
	v_rcp_f32_e32 v166, v166
	v_rcp_f32_e32 v167, v167
	v_rcp_f32_e32 v168, v168
	v_rcp_f32_e32 v169, v169
	v_add_u32_e32 v140, 0x58000, v239
	v_add_u32_e32 v174, 0x84000, v239
	v_pk_mul_f32 v[92:93], v[92:93], v[128:129]
	v_pk_mul_f32 v[94:95], v[94:95], v[130:131]
	v_pk_mul_f32 v[84:85], v[84:85], v[132:133]
	v_pk_mul_f32 v[86:87], v[86:87], v[134:135]
	v_pk_mul_f32 v[76:77], v[76:77], v[162:163]
	v_pk_mul_f32 v[78:79], v[78:79], v[164:165]
	v_pk_mul_f32 v[68:69], v[68:69], v[166:167]
	v_pk_mul_f32 v[70:71], v[70:71], v[168:169]
	v_pk_mul_f32 v[92:93], v[92:93], v[88:89]
	v_pk_mul_f32 v[94:95], v[94:95], v[90:91]
	v_pk_mul_f32 v[84:85], v[84:85], v[80:81]
	v_pk_mul_f32 v[86:87], v[86:87], v[82:83]
	v_pk_mul_f32 v[76:77], v[76:77], v[72:73]
	v_pk_mul_f32 v[78:79], v[78:79], v[74:75]
	v_pk_mul_f32 v[68:69], v[68:69], v[64:65]
	v_pk_mul_f32 v[70:71], v[70:71], v[66:67]
	v_cvt_pk_bf16_f32 v136, v92, v93
	v_cvt_pk_bf16_f32 v137, v94, v95
	v_cvt_pk_bf16_f32 v138, v84, v85
	v_cvt_pk_bf16_f32 v139, v86, v87
	v_cvt_pk_bf16_f32 v170, v76, v77
	v_cvt_pk_bf16_f32 v171, v78, v79
	v_cvt_pk_bf16_f32 v172, v68, v69
	v_cvt_pk_bf16_f32 v173, v70, v71
	global_store_dwordx4 v140, v[136:139], s[28:29]
	global_store_dwordx4 v174, v[170:173], s[28:29]
	s_nop 1
	v_pk_mul_f32 v[60:61], v[60:61], v[228:229] op_sel_hi:[1,0]
	v_pk_mul_f32 v[62:63], v[62:63], v[228:229] op_sel_hi:[1,0]
	v_pk_mul_f32 v[52:53], v[52:53], v[228:229] op_sel_hi:[1,0]
	v_pk_mul_f32 v[54:55], v[54:55], v[228:229] op_sel_hi:[1,0]
	v_pk_mul_f32 v[44:45], v[44:45], v[230:231] op_sel_hi:[1,0]
	v_pk_mul_f32 v[46:47], v[46:47], v[230:231] op_sel_hi:[1,0]
	v_pk_mul_f32 v[36:37], v[36:37], v[230:231] op_sel_hi:[1,0]
	v_pk_mul_f32 v[38:39], v[38:39], v[230:231] op_sel_hi:[1,0]
	v_pk_mul_f32 v[128:129], v[60:61], v[236:237] op_sel_hi:[1,0]
	v_pk_mul_f32 v[130:131], v[62:63], v[236:237] op_sel_hi:[1,0]
	v_pk_mul_f32 v[132:133], v[52:53], v[236:237] op_sel_hi:[1,0]
	v_pk_mul_f32 v[134:135], v[54:55], v[236:237] op_sel_hi:[1,0]
	v_pk_mul_f32 v[162:163], v[44:45], v[236:237] op_sel_hi:[1,0]
	v_pk_mul_f32 v[164:165], v[46:47], v[236:237] op_sel_hi:[1,0]
	v_pk_mul_f32 v[166:167], v[36:37], v[236:237] op_sel_hi:[1,0]
	v_pk_mul_f32 v[168:169], v[38:39], v[236:237] op_sel_hi:[1,0]
	v_exp_f32_e32 v128, v128
	v_exp_f32_e32 v129, v129
	v_exp_f32_e32 v130, v130
	v_exp_f32_e32 v131, v131
	v_exp_f32_e32 v132, v132
	v_exp_f32_e32 v133, v133
	v_exp_f32_e32 v134, v134
	v_exp_f32_e32 v135, v135
	v_exp_f32_e32 v162, v162
	v_exp_f32_e32 v163, v163
	v_exp_f32_e32 v164, v164
	v_exp_f32_e32 v165, v165
	v_exp_f32_e32 v166, v166
	v_exp_f32_e32 v167, v167
	v_exp_f32_e32 v168, v168
	v_exp_f32_e32 v169, v169
	v_pk_mul_f32 v[56:57], v[56:57], v[228:229] op_sel_hi:[1,0]
	v_pk_mul_f32 v[58:59], v[58:59], v[228:229] op_sel_hi:[1,0]
	v_pk_mul_f32 v[48:49], v[48:49], v[228:229] op_sel_hi:[1,0]
	v_pk_mul_f32 v[50:51], v[50:51], v[228:229] op_sel_hi:[1,0]
	v_pk_mul_f32 v[40:41], v[40:41], v[230:231] op_sel_hi:[1,0]
	v_pk_mul_f32 v[42:43], v[42:43], v[230:231] op_sel_hi:[1,0]
	v_pk_mul_f32 v[32:33], v[32:33], v[230:231] op_sel_hi:[1,0]
	v_pk_mul_f32 v[34:35], v[34:35], v[230:231] op_sel_hi:[1,0]
	v_pk_add_f32 v[128:129], v[128:129], 1.0 op_sel_hi:[1,0]
; __device__ __forceinline__ unsigned cvt_pk_bf16(float lo, float hi) { unsigned r; asm volatile("v_cvt_pk_bf16_f32 %0, %1, %2" : "=v"(r) : "v"(lo), "v"(hi)); return r; }
; __device__ __forceinline__ float sigmoidf_(float x) { return fast_rcp(1.0f + fast_exp2(-1.4426950408889634f * x)); }
; __device__ __forceinline__ void load_rstd(const float* part, int row0, int fq, float (&rs)[2][4]) {
;     ...
;         for (int m = 0; m < 4; ++m) { const float* p = part + (size_t)(row0 + ai * HALF + m * 16) * NPART + fq * 8;
;             const f32x4 a = *(const f32x4*)p, b = *(const f32x4*)(p + 4); float s = ((a[0] + a[1]) + (a[2] + a[3])) + ((b[0] + b[1]) + (b[2] + b[3]));
;             s += __shfl_xor(s, 16); s += __shfl_xor(s, 32); rs[ai][m] = rsqrtf(s * (1.0f / D) + RMS_EPS); }
;     __device__ __forceinline__ void operator()(const f32x4 (&acc)[2][2][4][2], const Unit& u, int wr, int wc, int fr, int fq) const {
;     ...
;             for (int m = 0; m < 4; ++m) { const float sc = rs[ai][m]; f32x4 o[2];
; #pragma unroll
;                 for (int n = 0; n < 2; ++n) { const f32x4 g = acc[ai][0][m][n] * sc, up = acc[ai][1][m][n] * sc;
; #pragma unroll
;                     for (int e = 0; e < 4; ++e) o[n][e] = g[e] * sigmoidf_(g[e]) * up[e]; }
;                 u32x4 w; w.x = cvt_pk_bf16(o[0][0], o[0][1]); w.y = cvt_pk_bf16(o[0][2], o[0][3]); w.z = cvt_pk_bf16(o[1][0], o[1][1]); w.w = cvt_pk_bf16(o[1][2], o[1][3]);
;                 *(u32x4*)(O + (size_t)(row0 + ai * HALF + m * 16) * FF + col0) = w; }
	v_pk_add_f32 v[130:131], v[130:131], 1.0 op_sel_hi:[1,0]
	v_pk_add_f32 v[132:133], v[132:133], 1.0 op_sel_hi:[1,0]
	v_pk_add_f32 v[134:135], v[134:135], 1.0 op_sel_hi:[1,0]
	v_pk_add_f32 v[162:163], v[162:163], 1.0 op_sel_hi:[1,0]
	v_pk_add_f32 v[164:165], v[164:165], 1.0 op_sel_hi:[1,0]
	v_pk_add_f32 v[166:167], v[166:167], 1.0 op_sel_hi:[1,0]
	v_pk_add_f32 v[168:169], v[168:169], 1.0 op_sel_hi:[1,0]
	v_rcp_f32_e32 v128, v128
	v_rcp_f32_e32 v129, v129
	v_rcp_f32_e32 v130, v130
	v_rcp_f32_e32 v131, v131
	v_rcp_f32_e32 v132, v132
	v_rcp_f32_e32 v133, v133
	v_rcp_f32_e32 v134, v134
	v_rcp_f32_e32 v135, v135
	v_rcp_f32_e32 v162, v162
	v_rcp_f32_e32 v163, v163
	v_rcp_f32_e32 v164, v164
	v_rcp_f32_e32 v165, v165
	v_rcp_f32_e32 v166, v166
	v_rcp_f32_e32 v167, v167
	v_rcp_f32_e32 v168, v168
	v_rcp_f32_e32 v169, v169
	v_add_u32_e32 v140, 0x160000, v239
	v_add_u32_e32 v174, 0x18c000, v239
	v_pk_mul_f32 v[60:61], v[60:61], v[128:129]
	v_pk_mul_f32 v[62:63], v[62:63], v[130:131]
	v_pk_mul_f32 v[52:53], v[52:53], v[132:133]
	v_pk_mul_f32 v[54:55], v[54:55], v[134:135]
	v_pk_mul_f32 v[44:45], v[44:45], v[162:163]
	v_pk_mul_f32 v[46:47], v[46:47], v[164:165]
	v_pk_mul_f32 v[36:37], v[36:37], v[166:167]
	v_pk_mul_f32 v[38:39], v[38:39], v[168:169]
	v_pk_mul_f32 v[60:61], v[60:61], v[56:57]
	v_pk_mul_f32 v[62:63], v[62:63], v[58:59]
	v_pk_mul_f32 v[52:53], v[52:53], v[48:49]
	v_pk_mul_f32 v[54:55], v[54:55], v[50:51]
	v_pk_mul_f32 v[44:45], v[44:45], v[40:41]
	v_pk_mul_f32 v[46:47], v[46:47], v[42:43]
	v_pk_mul_f32 v[36:37], v[36:37], v[32:33]
	v_pk_mul_f32 v[38:39], v[38:39], v[34:35]
	v_cvt_pk_bf16_f32 v136, v60, v61
	v_cvt_pk_bf16_f32 v137, v62, v63
	v_cvt_pk_bf16_f32 v138, v52, v53
	v_cvt_pk_bf16_f32 v139, v54, v55
	v_cvt_pk_bf16_f32 v170, v44, v45
	v_cvt_pk_bf16_f32 v171, v46, v47
	v_cvt_pk_bf16_f32 v172, v36, v37
	v_cvt_pk_bf16_f32 v173, v38, v39
	global_store_dwordx4 v140, v[136:139], s[28:29]
	global_store_dwordx4 v174, v[170:173], s[28:29]
	s_nop 1
	v_pk_mul_f32 v[28:29], v[28:29], v[232:233] op_sel_hi:[1,0]
	v_pk_mul_f32 v[30:31], v[30:31], v[232:233] op_sel_hi:[1,0]
	v_pk_mul_f32 v[20:21], v[20:21], v[232:233] op_sel_hi:[1,0]
	v_pk_mul_f32 v[22:23], v[22:23], v[232:233] op_sel_hi:[1,0]
	v_pk_mul_f32 v[12:13], v[12:13], v[234:235] op_sel_hi:[1,0]
	v_pk_mul_f32 v[14:15], v[14:15], v[234:235] op_sel_hi:[1,0]
	v_pk_mul_f32 v[4:5], v[4:5], v[234:235] op_sel_hi:[1,0]
	v_pk_mul_f32 v[6:7], v[6:7], v[234:235] op_sel_hi:[1,0]
	v_pk_mul_f32 v[128:129], v[28:29], v[236:237] op_sel_hi:[1,0]
	v_pk_mul_f32 v[130:131], v[30:31], v[236:237] op_sel_hi:[1,0]
	v_pk_mul_f32 v[132:133], v[20:21], v[236:237] op_sel_hi:[1,0]
	v_pk_mul_f32 v[134:135], v[22:23], v[236:237] op_sel_hi:[1,0]
	v_pk_mul_f32 v[162:163], v[12:13], v[236:237] op_sel_hi:[1,0]
	v_pk_mul_f32 v[164:165], v[14:15], v[236:237] op_sel_hi:[1,0]
	v_pk_mul_f32 v[166:167], v[4:5], v[236:237] op_sel_hi:[1,0]
	v_pk_mul_f32 v[168:169], v[6:7], v[236:237] op_sel_hi:[1,0]
	v_exp_f32_e32 v128, v128
	v_exp_f32_e32 v129, v129
	v_exp_f32_e32 v130, v130
	v_exp_f32_e32 v131, v131
	v_exp_f32_e32 v132, v132
	v_exp_f32_e32 v133, v133
	v_exp_f32_e32 v134, v134
	v_exp_f32_e32 v135, v135
	v_exp_f32_e32 v162, v162
	v_exp_f32_e32 v163, v163
	v_exp_f32_e32 v164, v164
	v_exp_f32_e32 v165, v165
	v_exp_f32_e32 v166, v166
	v_exp_f32_e32 v167, v167
	v_exp_f32_e32 v168, v168
	v_exp_f32_e32 v169, v169
	v_pk_mul_f32 v[24:25], v[24:25], v[232:233] op_sel_hi:[1,0]
	v_pk_mul_f32 v[26:27], v[26:27], v[232:233] op_sel_hi:[1,0]
	v_pk_mul_f32 v[16:17], v[16:17], v[232:233] op_sel_hi:[1,0]
	v_pk_mul_f32 v[18:19], v[18:19], v[232:233] op_sel_hi:[1,0]
	v_pk_mul_f32 v[8:9], v[8:9], v[234:235] op_sel_hi:[1,0]
	v_pk_mul_f32 v[10:11], v[10:11], v[234:235] op_sel_hi:[1,0]
	v_pk_mul_f32 v[0:1], v[0:1], v[234:235] op_sel_hi:[1,0]
	v_pk_mul_f32 v[2:3], v[2:3], v[234:235] op_sel_hi:[1,0]
	v_pk_add_f32 v[128:129], v[128:129], 1.0 op_sel_hi:[1,0]
	v_pk_add_f32 v[130:131], v[130:131], 1.0 op_sel_hi:[1,0]
	v_pk_add_f32 v[132:133], v[132:133], 1.0 op_sel_hi:[1,0]
	v_pk_add_f32 v[134:135], v[134:135], 1.0 op_sel_hi:[1,0]
	v_pk_add_f32 v[162:163], v[162:163], 1.0 op_sel_hi:[1,0]
	v_pk_add_f32 v[164:165], v[164:165], 1.0 op_sel_hi:[1,0]
	v_pk_add_f32 v[166:167], v[166:167], 1.0 op_sel_hi:[1,0]
	v_pk_add_f32 v[168:169], v[168:169], 1.0 op_sel_hi:[1,0]
	v_rcp_f32_e32 v128, v128
	v_rcp_f32_e32 v129, v129
	v_rcp_f32_e32 v130, v130
	v_rcp_f32_e32 v131, v131
	v_rcp_f32_e32 v132, v132
	v_rcp_f32_e32 v133, v133
	v_rcp_f32_e32 v134, v134
	v_rcp_f32_e32 v135, v135
	v_rcp_f32_e32 v162, v162
	v_rcp_f32_e32 v163, v163
	v_rcp_f32_e32 v164, v164
	v_rcp_f32_e32 v165, v165
	v_rcp_f32_e32 v166, v166
	v_rcp_f32_e32 v167, v167
	v_rcp_f32_e32 v168, v168
	v_rcp_f32_e32 v169, v169
	v_add_u32_e32 v140, 0x1b8000, v239
	v_add_u32_e32 v174, 0x1e4000, v239
	v_pk_mul_f32 v[28:29], v[28:29], v[128:129]
	v_pk_mul_f32 v[30:31], v[30:31], v[130:131]
	v_pk_mul_f32 v[20:21], v[20:21], v[132:133]
	v_pk_mul_f32 v[22:23], v[22:23], v[134:135]
	v_pk_mul_f32 v[12:13], v[12:13], v[162:163]
	v_pk_mul_f32 v[14:15], v[14:15], v[164:165]
	v_pk_mul_f32 v[4:5], v[4:5], v[166:167]
	v_pk_mul_f32 v[6:7], v[6:7], v[168:169]
	v_pk_mul_f32 v[28:29], v[28:29], v[24:25]
	v_pk_mul_f32 v[30:31], v[30:31], v[26:27]
	v_pk_mul_f32 v[20:21], v[20:21], v[16:17]
	v_pk_mul_f32 v[22:23], v[22:23], v[18:19]
	v_pk_mul_f32 v[12:13], v[12:13], v[8:9]
	v_pk_mul_f32 v[14:15], v[14:15], v[10:11]
	v_pk_mul_f32 v[4:5], v[4:5], v[0:1]
	v_pk_mul_f32 v[6:7], v[6:7], v[2:3]
	v_cvt_pk_bf16_f32 v136, v28, v29
	v_cvt_pk_bf16_f32 v137, v30, v31
	v_cvt_pk_bf16_f32 v138, v20, v21
	v_cvt_pk_bf16_f32 v139, v22, v23
	v_cvt_pk_bf16_f32 v170, v12, v13
	v_cvt_pk_bf16_f32 v171, v14, v15
	v_cvt_pk_bf16_f32 v172, v4, v5
	v_cvt_pk_bf16_f32 v173, v6, v7
	global_store_dwordx4 v140, v[136:139], s[28:29]
	global_store_dwordx4 v174, v[170:173], s[28:29]
	s_cmp_lg_u64 s[2:3], 0
	s_cbranch_scc0 .Lswg_nf_SWG_LBB0_1151
	s_waitcnt vmcnt(8)
	v_add_f32_e32 v188, v188, v189
	v_add_f32_e32 v190, v190, v191
	v_add_f32_e32 v192, v192, v193
	v_add_f32_e32 v194, v194, v195
	v_add_f32_e32 v196, v196, v197
	v_add_f32_e32 v198, v198, v199
	v_add_f32_e32 v200, v200, v201
	v_add_f32_e32 v202, v202, v203
	v_add_f32_e32 v188, v188, v190
	v_add_f32_e32 v192, v192, v194
	v_add_f32_e32 v196, v196, v198
	v_add_f32_e32 v200, v200, v202
	v_add_f32_e32 v188, v188, v192
	v_add_f32_e32 v196, v196, v200
	v_add_f32_e32 v188, v188, v196
	s_nop 1
	v_add_f32_dpp v192, v188, v188 quad_perm:[1,0,3,2] row_mask:0xf bank_mask:0xf
	v_fmamk_f32 v192, v192, 0x3a000000, v238
	v_rsq_f32_e32 v192, v192
	s_and_b32 s96, s99, 1
	s_xor_b32 s96, s96, 1
	s_lshl_b32 s96, s96, 10
	s_lshl_b32 s97, s95, 7
	s_add_i32 s96, s96, s97
	s_add_i32 s96, s96, 0x21000
	v_lshrrev_b32_e32 v204, 1, v220
	v_lshl_add_u32 v204, v204, 2, s96
	ds_write_b32 v204, v192
	s_and_b32 s99, s99, 1
	s_xor_b32 s99, s99, 3
	s_branch .Lswg_end_SWG_LBB0_1151

; #define PG8_BAR __builtin_amdgcn_s_barrier()
; template <class Epi, class Sched, bool ALIGN_EPI>
; __device__ __forceinline__ void gemm_phase(LAS unsigned char* lds, const Gemm g, const Sched& S, const Epi& E) {
;     ...
;         if (!has_next) break;
; #pragma unroll
;         for (int a = 0; a < 2; ++a)
; #pragma unroll
;             for (int b = 0; b < 2; ++b)
; #pragma unroll
;                 for (int m = 0; m < 4; ++m)
; #pragma unroll
;                     for (int n = 0; n < 2; ++n) acc[a][b][m][n] = (f32x4){0.f, 0.f, 0.f, 0.f};
;         cur = nxt; cA = nA; cB = nB; ++ui;
;         if constexpr (ALIGN_EPI) { if (wr == 1) PG8_BAR; }
.Lswg_end_SWG_LBB0_1151:
	s_andn2_b64 vcc, exec, s[2:3]
	s_mov_b64 s[2:3], -1
	s_cbranch_vccnz .LBB0_1144
	s_andn2_b64 vcc, exec, s[24:25]
	s_cbranch_vccnz .LBB0_1143
	s_barrier
	s_branch .LBB0_1143
